# p_mod silu(c) LDS fill: 20 serialized load-wait iterations replaced by 20 loads issued up front with counted waits (same arithmetic)
# speedup vs baseline: 1.0148x; 1.0010x over previous
; #define LAS __attribute__((address_space(3)))
;     DI const float* inp(int i) const { return as_global(P.in[i]); }
; DI void p_mod(const Frame& F) {
;     LAS float* sv = (LAS float*)F.lds; LAS float* red = sv + 5 * 2048;
;     const float* c = F.inp(1); const float* cc = F.inp(3);
;     for (int i = F.tid; i < 5 * 2048; i += NT) { const int r = i >> 11, k = i & 2047; const float v = r < 4 ? c[r * 2048 + k] : cc[k]; sv[i] = v / (1.f + __expf(-v)); }
.LBB0_43:
	s_waitcnt vmcnt(0)
	v_and_b32_e32 v0, 0x7ff, v5
	v_lshlrev_b32_e32 v0, 2, v0
	v_lshl_add_u64 v[6:7], s[42:43], 0, v[0:1]
	v_cmp_gt_i32_e32 vcc, s20, v5
	s_nop 1
	v_cndmask_b32_e32 v7, v7, v3, vcc
	v_cndmask_b32_e32 v6, v6, v2, vcc
	global_load_dword v84, v[6:7], off
	v_add_u32_e32 v5, 0x200, v5
	v_lshl_add_u64 v[2:3], v[2:3], 0, s[28:29]
	v_and_b32_e32 v0, 0x7ff, v5
	v_lshlrev_b32_e32 v0, 2, v0
	v_lshl_add_u64 v[6:7], s[42:43], 0, v[0:1]
	v_cmp_gt_i32_e32 vcc, s20, v5
	s_nop 1
	v_cndmask_b32_e32 v7, v7, v3, vcc
	v_cndmask_b32_e32 v6, v6, v2, vcc
	global_load_dword v85, v[6:7], off
	v_add_u32_e32 v5, 0x200, v5
	v_lshl_add_u64 v[2:3], v[2:3], 0, s[28:29]
	v_and_b32_e32 v0, 0x7ff, v5
	v_lshlrev_b32_e32 v0, 2, v0
	v_lshl_add_u64 v[6:7], s[42:43], 0, v[0:1]
	v_cmp_gt_i32_e32 vcc, s20, v5
	s_nop 1
	v_cndmask_b32_e32 v7, v7, v3, vcc
	v_cndmask_b32_e32 v6, v6, v2, vcc
	global_load_dword v86, v[6:7], off
	v_add_u32_e32 v5, 0x200, v5
	v_lshl_add_u64 v[2:3], v[2:3], 0, s[28:29]
	v_and_b32_e32 v0, 0x7ff, v5
	v_lshlrev_b32_e32 v0, 2, v0
	v_lshl_add_u64 v[6:7], s[42:43], 0, v[0:1]
	v_cmp_gt_i32_e32 vcc, s20, v5
	s_nop 1
	v_cndmask_b32_e32 v7, v7, v3, vcc
	v_cndmask_b32_e32 v6, v6, v2, vcc
	global_load_dword v87, v[6:7], off
	v_add_u32_e32 v5, 0x200, v5
	v_lshl_add_u64 v[2:3], v[2:3], 0, s[28:29]
	v_and_b32_e32 v0, 0x7ff, v5
	v_lshlrev_b32_e32 v0, 2, v0
	v_lshl_add_u64 v[6:7], s[42:43], 0, v[0:1]
	v_cmp_gt_i32_e32 vcc, s20, v5
	s_nop 1
	v_cndmask_b32_e32 v7, v7, v3, vcc
	v_cndmask_b32_e32 v6, v6, v2, vcc
	global_load_dword v88, v[6:7], off
	v_add_u32_e32 v5, 0x200, v5
	v_lshl_add_u64 v[2:3], v[2:3], 0, s[28:29]
	v_and_b32_e32 v0, 0x7ff, v5
	v_lshlrev_b32_e32 v0, 2, v0
	v_lshl_add_u64 v[6:7], s[42:43], 0, v[0:1]
	v_cmp_gt_i32_e32 vcc, s20, v5
	s_nop 1
	v_cndmask_b32_e32 v7, v7, v3, vcc
	v_cndmask_b32_e32 v6, v6, v2, vcc
	global_load_dword v89, v[6:7], off
	v_add_u32_e32 v5, 0x200, v5
	v_lshl_add_u64 v[2:3], v[2:3], 0, s[28:29]
	v_and_b32_e32 v0, 0x7ff, v5
	v_lshlrev_b32_e32 v0, 2, v0
	v_lshl_add_u64 v[6:7], s[42:43], 0, v[0:1]
	v_cmp_gt_i32_e32 vcc, s20, v5
	s_nop 1
	v_cndmask_b32_e32 v7, v7, v3, vcc
	v_cndmask_b32_e32 v6, v6, v2, vcc
	global_load_dword v90, v[6:7], off
	v_add_u32_e32 v5, 0x200, v5
	v_lshl_add_u64 v[2:3], v[2:3], 0, s[28:29]
	v_and_b32_e32 v0, 0x7ff, v5
	v_lshlrev_b32_e32 v0, 2, v0
	v_lshl_add_u64 v[6:7], s[42:43], 0, v[0:1]
	v_cmp_gt_i32_e32 vcc, s20, v5
	s_nop 1
	v_cndmask_b32_e32 v7, v7, v3, vcc
	v_cndmask_b32_e32 v6, v6, v2, vcc
	global_load_dword v91, v[6:7], off
	v_add_u32_e32 v5, 0x200, v5
	v_lshl_add_u64 v[2:3], v[2:3], 0, s[28:29]
	v_and_b32_e32 v0, 0x7ff, v5
	v_lshlrev_b32_e32 v0, 2, v0
	v_lshl_add_u64 v[6:7], s[42:43], 0, v[0:1]
	v_cmp_gt_i32_e32 vcc, s20, v5
	s_nop 1
	v_cndmask_b32_e32 v7, v7, v3, vcc
	v_cndmask_b32_e32 v6, v6, v2, vcc
	global_load_dword v92, v[6:7], off
	v_add_u32_e32 v5, 0x200, v5
	v_lshl_add_u64 v[2:3], v[2:3], 0, s[28:29]
	v_and_b32_e32 v0, 0x7ff, v5
	v_lshlrev_b32_e32 v0, 2, v0
	v_lshl_add_u64 v[6:7], s[42:43], 0, v[0:1]
	v_cmp_gt_i32_e32 vcc, s20, v5
	s_nop 1
	v_cndmask_b32_e32 v7, v7, v3, vcc
	v_cndmask_b32_e32 v6, v6, v2, vcc
	global_load_dword v93, v[6:7], off
	v_add_u32_e32 v5, 0x200, v5
	v_lshl_add_u64 v[2:3], v[2:3], 0, s[28:29]
	v_and_b32_e32 v0, 0x7ff, v5
	v_lshlrev_b32_e32 v0, 2, v0
	v_lshl_add_u64 v[6:7], s[42:43], 0, v[0:1]
	v_cmp_gt_i32_e32 vcc, s20, v5
	s_nop 1
	v_cndmask_b32_e32 v7, v7, v3, vcc
	v_cndmask_b32_e32 v6, v6, v2, vcc
	global_load_dword v94, v[6:7], off
	v_add_u32_e32 v5, 0x200, v5
	v_lshl_add_u64 v[2:3], v[2:3], 0, s[28:29]
	v_and_b32_e32 v0, 0x7ff, v5
	v_lshlrev_b32_e32 v0, 2, v0
	v_lshl_add_u64 v[6:7], s[42:43], 0, v[0:1]
	v_cmp_gt_i32_e32 vcc, s20, v5
	s_nop 1
	v_cndmask_b32_e32 v7, v7, v3, vcc
	v_cndmask_b32_e32 v6, v6, v2, vcc
	global_load_dword v95, v[6:7], off
	v_add_u32_e32 v5, 0x200, v5
	v_lshl_add_u64 v[2:3], v[2:3], 0, s[28:29]
	v_and_b32_e32 v0, 0x7ff, v5
	v_lshlrev_b32_e32 v0, 2, v0
	v_lshl_add_u64 v[6:7], s[42:43], 0, v[0:1]
	v_cmp_gt_i32_e32 vcc, s20, v5
	s_nop 1
	v_cndmask_b32_e32 v7, v7, v3, vcc
	v_cndmask_b32_e32 v6, v6, v2, vcc
	global_load_dword v96, v[6:7], off
	v_add_u32_e32 v5, 0x200, v5
	v_lshl_add_u64 v[2:3], v[2:3], 0, s[28:29]
	v_and_b32_e32 v0, 0x7ff, v5
	v_lshlrev_b32_e32 v0, 2, v0
	v_lshl_add_u64 v[6:7], s[42:43], 0, v[0:1]
	v_cmp_gt_i32_e32 vcc, s20, v5
	s_nop 1
	v_cndmask_b32_e32 v7, v7, v3, vcc
	v_cndmask_b32_e32 v6, v6, v2, vcc
	global_load_dword v97, v[6:7], off
	v_add_u32_e32 v5, 0x200, v5
	v_lshl_add_u64 v[2:3], v[2:3], 0, s[28:29]
	v_and_b32_e32 v0, 0x7ff, v5
	v_lshlrev_b32_e32 v0, 2, v0
	v_lshl_add_u64 v[6:7], s[42:43], 0, v[0:1]
	v_cmp_gt_i32_e32 vcc, s20, v5
	s_nop 1
	v_cndmask_b32_e32 v7, v7, v3, vcc
	v_cndmask_b32_e32 v6, v6, v2, vcc
	global_load_dword v98, v[6:7], off
	v_add_u32_e32 v5, 0x200, v5
	v_lshl_add_u64 v[2:3], v[2:3], 0, s[28:29]
	v_and_b32_e32 v0, 0x7ff, v5
	v_lshlrev_b32_e32 v0, 2, v0
	v_lshl_add_u64 v[6:7], s[42:43], 0, v[0:1]
	v_cmp_gt_i32_e32 vcc, s20, v5
	s_nop 1
	v_cndmask_b32_e32 v7, v7, v3, vcc
	v_cndmask_b32_e32 v6, v6, v2, vcc
	global_load_dword v99, v[6:7], off
	v_add_u32_e32 v5, 0x200, v5
	v_lshl_add_u64 v[2:3], v[2:3], 0, s[28:29]
	v_and_b32_e32 v0, 0x7ff, v5
	v_lshlrev_b32_e32 v0, 2, v0
	v_lshl_add_u64 v[6:7], s[42:43], 0, v[0:1]
	v_cmp_gt_i32_e32 vcc, s20, v5
	s_nop 1
	v_cndmask_b32_e32 v7, v7, v3, vcc
	v_cndmask_b32_e32 v6, v6, v2, vcc
	global_load_dword v100, v[6:7], off
	v_add_u32_e32 v5, 0x200, v5
	v_lshl_add_u64 v[2:3], v[2:3], 0, s[28:29]
	v_and_b32_e32 v0, 0x7ff, v5
	v_lshlrev_b32_e32 v0, 2, v0
	v_lshl_add_u64 v[6:7], s[42:43], 0, v[0:1]
	v_cmp_gt_i32_e32 vcc, s20, v5
	s_nop 1
	v_cndmask_b32_e32 v7, v7, v3, vcc
	v_cndmask_b32_e32 v6, v6, v2, vcc
	global_load_dword v101, v[6:7], off
	v_add_u32_e32 v5, 0x200, v5
	v_lshl_add_u64 v[2:3], v[2:3], 0, s[28:29]
	v_and_b32_e32 v0, 0x7ff, v5
	v_lshlrev_b32_e32 v0, 2, v0
	v_lshl_add_u64 v[6:7], s[42:43], 0, v[0:1]
	v_cmp_gt_i32_e32 vcc, s20, v5
	s_nop 1
	v_cndmask_b32_e32 v7, v7, v3, vcc
	v_cndmask_b32_e32 v6, v6, v2, vcc
	global_load_dword v102, v[6:7], off
	v_add_u32_e32 v5, 0x200, v5
	v_lshl_add_u64 v[2:3], v[2:3], 0, s[28:29]
	v_and_b32_e32 v0, 0x7ff, v5
	v_lshlrev_b32_e32 v0, 2, v0
	v_lshl_add_u64 v[6:7], s[42:43], 0, v[0:1]
	v_cmp_gt_i32_e32 vcc, s20, v5
	s_nop 1
	v_cndmask_b32_e32 v7, v7, v3, vcc
	v_cndmask_b32_e32 v6, v6, v2, vcc
	global_load_dword v103, v[6:7], off
	v_add_u32_e32 v5, 0x200, v5
	v_lshl_add_u64 v[2:3], v[2:3], 0, s[28:29]
	s_waitcnt vmcnt(19)
; DI void p_mod(const Frame& F) {
;     ...
;     for (int i = F.tid; i < 5 * 2048; i += NT) { const int r = i >> 11, k = i & 2047; const float v = r < 4 ? c[r * 2048 + k] : cc[k]; sv[i] = v / (1.f + __expf(-v)); }
	v_mov_b32_e32 v0, v84
	v_mul_f32_e32 v6, 0xbfb8aa3b, v0
	v_exp_f32_e32 v6, v6
	s_nop 0
	v_add_f32_e32 v6, 1.0, v6
	v_div_scale_f32 v7, s[6:7], v6, v6, v0
	v_rcp_f32_e32 v8, v7
	v_div_scale_f32 v9, vcc, v0, v6, v0
	v_fma_f32 v10, -v7, v8, 1.0
	v_fmac_f32_e32 v8, v10, v8
	v_mul_f32_e32 v10, v9, v8
	v_fma_f32 v11, -v7, v10, v9
	v_fmac_f32_e32 v10, v11, v8
	v_fma_f32 v7, -v7, v10, v9
	v_div_fmas_f32 v7, v7, v8, v10
	v_div_fixup_f32 v0, v7, v6, v0
	ds_write_b32 v4, v0
	v_add_u32_e32 v4, 0x800, v4
	s_waitcnt vmcnt(18)
	v_mov_b32_e32 v0, v85
	v_mul_f32_e32 v6, 0xbfb8aa3b, v0
	v_exp_f32_e32 v6, v6
	s_nop 0
	v_add_f32_e32 v6, 1.0, v6
	v_div_scale_f32 v7, s[6:7], v6, v6, v0
	v_rcp_f32_e32 v8, v7
	v_div_scale_f32 v9, vcc, v0, v6, v0
	v_fma_f32 v10, -v7, v8, 1.0
	v_fmac_f32_e32 v8, v10, v8
	v_mul_f32_e32 v10, v9, v8
	v_fma_f32 v11, -v7, v10, v9
	v_fmac_f32_e32 v10, v11, v8
	v_fma_f32 v7, -v7, v10, v9
	v_div_fmas_f32 v7, v7, v8, v10
	v_div_fixup_f32 v0, v7, v6, v0
	ds_write_b32 v4, v0
	v_add_u32_e32 v4, 0x800, v4
	s_waitcnt vmcnt(17)
	v_mov_b32_e32 v0, v86
	v_mul_f32_e32 v6, 0xbfb8aa3b, v0
	v_exp_f32_e32 v6, v6
	s_nop 0
	v_add_f32_e32 v6, 1.0, v6
	v_div_scale_f32 v7, s[6:7], v6, v6, v0
	v_rcp_f32_e32 v8, v7
	v_div_scale_f32 v9, vcc, v0, v6, v0
	v_fma_f32 v10, -v7, v8, 1.0
	v_fmac_f32_e32 v8, v10, v8
	v_mul_f32_e32 v10, v9, v8
	v_fma_f32 v11, -v7, v10, v9
	v_fmac_f32_e32 v10, v11, v8
	v_fma_f32 v7, -v7, v10, v9
	v_div_fmas_f32 v7, v7, v8, v10
	v_div_fixup_f32 v0, v7, v6, v0
	ds_write_b32 v4, v0
	v_add_u32_e32 v4, 0x800, v4
	s_waitcnt vmcnt(16)
	v_mov_b32_e32 v0, v87
	v_mul_f32_e32 v6, 0xbfb8aa3b, v0
	v_exp_f32_e32 v6, v6
	s_nop 0
	v_add_f32_e32 v6, 1.0, v6
	v_div_scale_f32 v7, s[6:7], v6, v6, v0
	v_rcp_f32_e32 v8, v7
	v_div_scale_f32 v9, vcc, v0, v6, v0
	v_fma_f32 v10, -v7, v8, 1.0
	v_fmac_f32_e32 v8, v10, v8
	v_mul_f32_e32 v10, v9, v8
	v_fma_f32 v11, -v7, v10, v9
	v_fmac_f32_e32 v10, v11, v8
	v_fma_f32 v7, -v7, v10, v9
	v_div_fmas_f32 v7, v7, v8, v10
	v_div_fixup_f32 v0, v7, v6, v0
	ds_write_b32 v4, v0
	v_add_u32_e32 v4, 0x800, v4
	s_waitcnt vmcnt(15)
	v_mov_b32_e32 v0, v88
	v_mul_f32_e32 v6, 0xbfb8aa3b, v0
	v_exp_f32_e32 v6, v6
	s_nop 0
	v_add_f32_e32 v6, 1.0, v6
	v_div_scale_f32 v7, s[6:7], v6, v6, v0
	v_rcp_f32_e32 v8, v7
	v_div_scale_f32 v9, vcc, v0, v6, v0
	v_fma_f32 v10, -v7, v8, 1.0
	v_fmac_f32_e32 v8, v10, v8
	v_mul_f32_e32 v10, v9, v8
	v_fma_f32 v11, -v7, v10, v9
	v_fmac_f32_e32 v10, v11, v8
	v_fma_f32 v7, -v7, v10, v9
	v_div_fmas_f32 v7, v7, v8, v10
	v_div_fixup_f32 v0, v7, v6, v0
	ds_write_b32 v4, v0
	v_add_u32_e32 v4, 0x800, v4
	s_waitcnt vmcnt(14)
	v_mov_b32_e32 v0, v89
	v_mul_f32_e32 v6, 0xbfb8aa3b, v0
	v_exp_f32_e32 v6, v6
	s_nop 0
	v_add_f32_e32 v6, 1.0, v6
	v_div_scale_f32 v7, s[6:7], v6, v6, v0
	v_rcp_f32_e32 v8, v7
	v_div_scale_f32 v9, vcc, v0, v6, v0
	v_fma_f32 v10, -v7, v8, 1.0
	v_fmac_f32_e32 v8, v10, v8
	v_mul_f32_e32 v10, v9, v8
	v_fma_f32 v11, -v7, v10, v9
	v_fmac_f32_e32 v10, v11, v8
	v_fma_f32 v7, -v7, v10, v9
	v_div_fmas_f32 v7, v7, v8, v10
	v_div_fixup_f32 v0, v7, v6, v0
	ds_write_b32 v4, v0
	v_add_u32_e32 v4, 0x800, v4
	s_waitcnt vmcnt(13)
	v_mov_b32_e32 v0, v90
	v_mul_f32_e32 v6, 0xbfb8aa3b, v0
	v_exp_f32_e32 v6, v6
	s_nop 0
	v_add_f32_e32 v6, 1.0, v6
	v_div_scale_f32 v7, s[6:7], v6, v6, v0
	v_rcp_f32_e32 v8, v7
	v_div_scale_f32 v9, vcc, v0, v6, v0
	v_fma_f32 v10, -v7, v8, 1.0
	v_fmac_f32_e32 v8, v10, v8
	v_mul_f32_e32 v10, v9, v8
	v_fma_f32 v11, -v7, v10, v9
	v_fmac_f32_e32 v10, v11, v8
	v_fma_f32 v7, -v7, v10, v9
	v_div_fmas_f32 v7, v7, v8, v10
	v_div_fixup_f32 v0, v7, v6, v0
	ds_write_b32 v4, v0
	v_add_u32_e32 v4, 0x800, v4
	s_waitcnt vmcnt(12)
	v_mov_b32_e32 v0, v91
	v_mul_f32_e32 v6, 0xbfb8aa3b, v0
	v_exp_f32_e32 v6, v6
	s_nop 0
	v_add_f32_e32 v6, 1.0, v6
	v_div_scale_f32 v7, s[6:7], v6, v6, v0
	v_rcp_f32_e32 v8, v7
	v_div_scale_f32 v9, vcc, v0, v6, v0
	v_fma_f32 v10, -v7, v8, 1.0
	v_fmac_f32_e32 v8, v10, v8
	v_mul_f32_e32 v10, v9, v8
	v_fma_f32 v11, -v7, v10, v9
	v_fmac_f32_e32 v10, v11, v8
	v_fma_f32 v7, -v7, v10, v9
	v_div_fmas_f32 v7, v7, v8, v10
	v_div_fixup_f32 v0, v7, v6, v0
	ds_write_b32 v4, v0
	v_add_u32_e32 v4, 0x800, v4
	s_waitcnt vmcnt(11)
	v_mov_b32_e32 v0, v92
	v_mul_f32_e32 v6, 0xbfb8aa3b, v0
	v_exp_f32_e32 v6, v6
	s_nop 0
	v_add_f32_e32 v6, 1.0, v6
	v_div_scale_f32 v7, s[6:7], v6, v6, v0
	v_rcp_f32_e32 v8, v7
	v_div_scale_f32 v9, vcc, v0, v6, v0
	v_fma_f32 v10, -v7, v8, 1.0
	v_fmac_f32_e32 v8, v10, v8
	v_mul_f32_e32 v10, v9, v8
	v_fma_f32 v11, -v7, v10, v9
	v_fmac_f32_e32 v10, v11, v8
	v_fma_f32 v7, -v7, v10, v9
	v_div_fmas_f32 v7, v7, v8, v10
	v_div_fixup_f32 v0, v7, v6, v0
	ds_write_b32 v4, v0
	v_add_u32_e32 v4, 0x800, v4
	s_waitcnt vmcnt(10)
	v_mov_b32_e32 v0, v93
	v_mul_f32_e32 v6, 0xbfb8aa3b, v0
	v_exp_f32_e32 v6, v6
	s_nop 0
	v_add_f32_e32 v6, 1.0, v6
	v_div_scale_f32 v7, s[6:7], v6, v6, v0
	v_rcp_f32_e32 v8, v7
	v_div_scale_f32 v9, vcc, v0, v6, v0
	v_fma_f32 v10, -v7, v8, 1.0
	v_fmac_f32_e32 v8, v10, v8
	v_mul_f32_e32 v10, v9, v8
	v_fma_f32 v11, -v7, v10, v9
	v_fmac_f32_e32 v10, v11, v8
	v_fma_f32 v7, -v7, v10, v9
	v_div_fmas_f32 v7, v7, v8, v10
	v_div_fixup_f32 v0, v7, v6, v0
	ds_write_b32 v4, v0
	v_add_u32_e32 v4, 0x800, v4
	s_waitcnt vmcnt(9)
; DI void p_mod(const Frame& F) {
;     ...
;     for (int i = F.tid; i < 5 * 2048; i += NT) { const int r = i >> 11, k = i & 2047; const float v = r < 4 ? c[r * 2048 + k] : cc[k]; sv[i] = v / (1.f + __expf(-v)); }
	v_mov_b32_e32 v0, v94
	v_mul_f32_e32 v6, 0xbfb8aa3b, v0
	v_exp_f32_e32 v6, v6
	s_nop 0
	v_add_f32_e32 v6, 1.0, v6
	v_div_scale_f32 v7, s[6:7], v6, v6, v0
	v_rcp_f32_e32 v8, v7
	v_div_scale_f32 v9, vcc, v0, v6, v0
	v_fma_f32 v10, -v7, v8, 1.0
	v_fmac_f32_e32 v8, v10, v8
	v_mul_f32_e32 v10, v9, v8
	v_fma_f32 v11, -v7, v10, v9
	v_fmac_f32_e32 v10, v11, v8
	v_fma_f32 v7, -v7, v10, v9
	v_div_fmas_f32 v7, v7, v8, v10
	v_div_fixup_f32 v0, v7, v6, v0
	ds_write_b32 v4, v0
	v_add_u32_e32 v4, 0x800, v4
	s_waitcnt vmcnt(8)
	v_mov_b32_e32 v0, v95
	v_mul_f32_e32 v6, 0xbfb8aa3b, v0
	v_exp_f32_e32 v6, v6
	s_nop 0
	v_add_f32_e32 v6, 1.0, v6
	v_div_scale_f32 v7, s[6:7], v6, v6, v0
	v_rcp_f32_e32 v8, v7
	v_div_scale_f32 v9, vcc, v0, v6, v0
	v_fma_f32 v10, -v7, v8, 1.0
	v_fmac_f32_e32 v8, v10, v8
	v_mul_f32_e32 v10, v9, v8
	v_fma_f32 v11, -v7, v10, v9
	v_fmac_f32_e32 v10, v11, v8
	v_fma_f32 v7, -v7, v10, v9
	v_div_fmas_f32 v7, v7, v8, v10
	v_div_fixup_f32 v0, v7, v6, v0
	ds_write_b32 v4, v0
	v_add_u32_e32 v4, 0x800, v4
	s_waitcnt vmcnt(7)
	v_mov_b32_e32 v0, v96
	v_mul_f32_e32 v6, 0xbfb8aa3b, v0
	v_exp_f32_e32 v6, v6
	s_nop 0
	v_add_f32_e32 v6, 1.0, v6
	v_div_scale_f32 v7, s[6:7], v6, v6, v0
	v_rcp_f32_e32 v8, v7
	v_div_scale_f32 v9, vcc, v0, v6, v0
	v_fma_f32 v10, -v7, v8, 1.0
	v_fmac_f32_e32 v8, v10, v8
	v_mul_f32_e32 v10, v9, v8
	v_fma_f32 v11, -v7, v10, v9
	v_fmac_f32_e32 v10, v11, v8
	v_fma_f32 v7, -v7, v10, v9
	v_div_fmas_f32 v7, v7, v8, v10
	v_div_fixup_f32 v0, v7, v6, v0
	ds_write_b32 v4, v0
	v_add_u32_e32 v4, 0x800, v4
	s_waitcnt vmcnt(6)
	v_mov_b32_e32 v0, v97
	v_mul_f32_e32 v6, 0xbfb8aa3b, v0
	v_exp_f32_e32 v6, v6
	s_nop 0
	v_add_f32_e32 v6, 1.0, v6
	v_div_scale_f32 v7, s[6:7], v6, v6, v0
	v_rcp_f32_e32 v8, v7
	v_div_scale_f32 v9, vcc, v0, v6, v0
	v_fma_f32 v10, -v7, v8, 1.0
	v_fmac_f32_e32 v8, v10, v8
	v_mul_f32_e32 v10, v9, v8
	v_fma_f32 v11, -v7, v10, v9
	v_fmac_f32_e32 v10, v11, v8
	v_fma_f32 v7, -v7, v10, v9
	v_div_fmas_f32 v7, v7, v8, v10
	v_div_fixup_f32 v0, v7, v6, v0
	ds_write_b32 v4, v0
	v_add_u32_e32 v4, 0x800, v4
	s_waitcnt vmcnt(5)
	v_mov_b32_e32 v0, v98
	v_mul_f32_e32 v6, 0xbfb8aa3b, v0
	v_exp_f32_e32 v6, v6
	s_nop 0
	v_add_f32_e32 v6, 1.0, v6
	v_div_scale_f32 v7, s[6:7], v6, v6, v0
	v_rcp_f32_e32 v8, v7
	v_div_scale_f32 v9, vcc, v0, v6, v0
	v_fma_f32 v10, -v7, v8, 1.0
	v_fmac_f32_e32 v8, v10, v8
	v_mul_f32_e32 v10, v9, v8
	v_fma_f32 v11, -v7, v10, v9
	v_fmac_f32_e32 v10, v11, v8
	v_fma_f32 v7, -v7, v10, v9
	v_div_fmas_f32 v7, v7, v8, v10
	v_div_fixup_f32 v0, v7, v6, v0
	ds_write_b32 v4, v0
	v_add_u32_e32 v4, 0x800, v4
	s_waitcnt vmcnt(4)
	v_mov_b32_e32 v0, v99
	v_mul_f32_e32 v6, 0xbfb8aa3b, v0
	v_exp_f32_e32 v6, v6
	s_nop 0
	v_add_f32_e32 v6, 1.0, v6
	v_div_scale_f32 v7, s[6:7], v6, v6, v0
	v_rcp_f32_e32 v8, v7
	v_div_scale_f32 v9, vcc, v0, v6, v0
	v_fma_f32 v10, -v7, v8, 1.0
	v_fmac_f32_e32 v8, v10, v8
	v_mul_f32_e32 v10, v9, v8
	v_fma_f32 v11, -v7, v10, v9
	v_fmac_f32_e32 v10, v11, v8
	v_fma_f32 v7, -v7, v10, v9
	v_div_fmas_f32 v7, v7, v8, v10
	v_div_fixup_f32 v0, v7, v6, v0
	ds_write_b32 v4, v0
	v_add_u32_e32 v4, 0x800, v4
	s_waitcnt vmcnt(3)
	v_mov_b32_e32 v0, v100
	v_mul_f32_e32 v6, 0xbfb8aa3b, v0
	v_exp_f32_e32 v6, v6
	s_nop 0
	v_add_f32_e32 v6, 1.0, v6
	v_div_scale_f32 v7, s[6:7], v6, v6, v0
	v_rcp_f32_e32 v8, v7
	v_div_scale_f32 v9, vcc, v0, v6, v0
	v_fma_f32 v10, -v7, v8, 1.0
	v_fmac_f32_e32 v8, v10, v8
	v_mul_f32_e32 v10, v9, v8
	v_fma_f32 v11, -v7, v10, v9
	v_fmac_f32_e32 v10, v11, v8
	v_fma_f32 v7, -v7, v10, v9
	v_div_fmas_f32 v7, v7, v8, v10
	v_div_fixup_f32 v0, v7, v6, v0
	ds_write_b32 v4, v0
	v_add_u32_e32 v4, 0x800, v4
	s_waitcnt vmcnt(2)
	v_mov_b32_e32 v0, v101
	v_mul_f32_e32 v6, 0xbfb8aa3b, v0
	v_exp_f32_e32 v6, v6
	s_nop 0
	v_add_f32_e32 v6, 1.0, v6
	v_div_scale_f32 v7, s[6:7], v6, v6, v0
	v_rcp_f32_e32 v8, v7
	v_div_scale_f32 v9, vcc, v0, v6, v0
	v_fma_f32 v10, -v7, v8, 1.0
	v_fmac_f32_e32 v8, v10, v8
	v_mul_f32_e32 v10, v9, v8
	v_fma_f32 v11, -v7, v10, v9
	v_fmac_f32_e32 v10, v11, v8
	v_fma_f32 v7, -v7, v10, v9
	v_div_fmas_f32 v7, v7, v8, v10
	v_div_fixup_f32 v0, v7, v6, v0
	ds_write_b32 v4, v0
	v_add_u32_e32 v4, 0x800, v4
	s_waitcnt vmcnt(1)
	v_mov_b32_e32 v0, v102
	v_mul_f32_e32 v6, 0xbfb8aa3b, v0
	v_exp_f32_e32 v6, v6
	s_nop 0
	v_add_f32_e32 v6, 1.0, v6
	v_div_scale_f32 v7, s[6:7], v6, v6, v0
	v_rcp_f32_e32 v8, v7
	v_div_scale_f32 v9, vcc, v0, v6, v0
	v_fma_f32 v10, -v7, v8, 1.0
	v_fmac_f32_e32 v8, v10, v8
	v_mul_f32_e32 v10, v9, v8
	v_fma_f32 v11, -v7, v10, v9
	v_fmac_f32_e32 v10, v11, v8
	v_fma_f32 v7, -v7, v10, v9
	v_div_fmas_f32 v7, v7, v8, v10
	v_div_fixup_f32 v0, v7, v6, v0
	ds_write_b32 v4, v0
	v_add_u32_e32 v4, 0x800, v4
	s_waitcnt vmcnt(0)
	v_mov_b32_e32 v0, v103
	v_mul_f32_e32 v6, 0xbfb8aa3b, v0
	v_exp_f32_e32 v6, v6
	s_nop 0
	v_add_f32_e32 v6, 1.0, v6
	v_div_scale_f32 v7, s[6:7], v6, v6, v0
	v_rcp_f32_e32 v8, v7
	v_div_scale_f32 v9, vcc, v0, v6, v0
	v_fma_f32 v10, -v7, v8, 1.0
	v_fmac_f32_e32 v8, v10, v8
	v_mul_f32_e32 v10, v9, v8
	v_fma_f32 v11, -v7, v10, v9
	v_fmac_f32_e32 v10, v11, v8
	v_fma_f32 v7, -v7, v10, v9
	v_div_fmas_f32 v7, v7, v8, v10
	v_div_fixup_f32 v0, v7, v6, v0
	ds_write_b32 v4, v0
	v_add_u32_e32 v4, 0x800, v4
